# v17 + hot loop heads (3 GEMM K-loops, 2 tail K-loops, attention tile loop) aligned to 64 B
# speedup vs baseline: 1.0037x; 1.0037x over previous
.LBB0_255:
	s_ashr_i32 s15, s14, 31
	s_lshl_b64 s[20:21], s[14:15], 19
	s_add_u32 s42, s31, s20
	s_addc_u32 s43, s34, s21
	s_and_b64 s[20:21], s[4:5], exec
	s_cselect_b32 s15, s43, s53
	s_cselect_b32 s20, s42, s52
	s_ashr_i32 s13, s12, 31
	s_lshl_b64 s[50:51], s[12:13], 19
	s_add_u32 s50, s35, s50
	s_addc_u32 s51, s36, s51
	s_and_b64 s[58:59], s[4:5], exec
	s_cselect_b32 s13, s51, s57
	s_cselect_b32 s21, s50, s56
	s_add_u32 s52, s52, 0x40080
	s_addc_u32 s53, s53, 0
	s_add_u32 s73, s56, 0x100
	s_addc_u32 s75, s57, 0
	s_mov_b32 s82, -2
	s_add_u32 s0, s52, 0xfffc0080
	s_addc_u32 s56, s53, -1
	s_add_i32 s83, 0, 0x10000
	s_cmp_eq_u32 s82, 12
	s_cselect_b32 s59, s15, s56
	s_cselect_b32 s58, s20, s0
	s_cselect_b32 s57, s13, s75
	s_cselect_b32 s56, s21, s73
	s_add_i32 s0, 0, 0x14000
	v_add_u32_e32 v94, s83, v171
	v_add_u32_e32 v155, s0, v171
	ds_read_b128 v[74:77], v94
	ds_read_b128 v[78:81], v94 offset:1024
	ds_read_b128 v[90:93], v94 offset:2048
	ds_read_b128 v[94:97], v94 offset:3072
	ds_read_b128 v[180:183], v155
	ds_read_b128 v[184:187], v155 offset:1024
	ds_read_b128 v[188:191], v155 offset:2048
	ds_read_b128 v[192:195], v155 offset:3072
	v_lshl_add_u64 v[168:169], s[52:53], 0, v[164:165]
	s_add_i32 m0, s61, 0xc000
	ds_read_b128 v[196:199], v177
	ds_read_b128 v[200:203], v177 offset:1024
	ds_read_b128 v[204:207], v177 offset:2048
	ds_read_b128 v[208:211], v177 offset:3072
	ds_read_b128 v[212:215], v177 offset:4096
	ds_read_b128 v[216:219], v177 offset:5120
	ds_read_b128 v[230:233], v177 offset:6144
	ds_read_b128 v[238:241], v177 offset:7168
	global_load_lds_dwordx4 v[168:169], off
	v_lshl_add_u64 v[168:169], s[52:53], 0, v[166:167]
	s_add_i32 m0, s61, 0xe000
	s_nop 0
	global_load_lds_dwordx4 v[168:169], off
	s_waitcnt vmcnt(8)
	s_waitcnt lgkmcnt(0)
	s_barrier
	s_setprio 1
	s_waitcnt lgkmcnt(0)
	v_mfma_f32_16x16x32_bf16 v[142:145], v[74:77], v[196:199], 0
	v_mfma_f32_16x16x32_bf16 v[134:137], v[90:93], v[196:199], 0
	v_mfma_f32_16x16x32_bf16 v[126:129], v[74:77], v[204:207], 0
	v_mfma_f32_16x16x32_bf16 v[118:121], v[90:93], v[204:207], 0
	v_mfma_f32_16x16x32_bf16 v[110:113], v[74:77], v[212:215], 0
	v_mfma_f32_16x16x32_bf16 v[102:105], v[90:93], v[212:215], 0
	v_mfma_f32_16x16x32_bf16 v[86:89], v[74:77], v[230:233], 0
	v_mfma_f32_16x16x32_bf16 v[70:73], v[90:93], v[230:233], 0
	v_mfma_f32_16x16x32_bf16 v[142:145], v[78:81], v[200:203], v[142:145]
	v_mfma_f32_16x16x32_bf16 v[134:137], v[94:97], v[200:203], v[134:137]
	v_mfma_f32_16x16x32_bf16 v[126:129], v[78:81], v[208:211], v[126:129]
	v_mfma_f32_16x16x32_bf16 v[118:121], v[94:97], v[208:211], v[118:121]
	v_mfma_f32_16x16x32_bf16 v[110:113], v[78:81], v[216:219], v[110:113]
	v_mfma_f32_16x16x32_bf16 v[102:105], v[94:97], v[216:219], v[102:105]
	v_mfma_f32_16x16x32_bf16 v[86:89], v[78:81], v[238:241], v[86:89]
	v_mfma_f32_16x16x32_bf16 v[70:73], v[94:97], v[238:241], v[70:73]
	s_setprio 0
	s_setprio 1
	v_mfma_f32_16x16x32_bf16 v[138:141], v[180:183], v[196:199], 0
	v_mfma_f32_16x16x32_bf16 v[130:133], v[188:191], v[196:199], 0
	v_mfma_f32_16x16x32_bf16 v[122:125], v[180:183], v[204:207], 0
	v_mfma_f32_16x16x32_bf16 v[114:117], v[188:191], v[204:207], 0
	v_mfma_f32_16x16x32_bf16 v[106:109], v[180:183], v[212:215], 0
	v_mfma_f32_16x16x32_bf16 v[98:101], v[188:191], v[212:215], 0
	v_mfma_f32_16x16x32_bf16 v[82:85], v[180:183], v[230:233], 0
	v_mfma_f32_16x16x32_bf16 v[66:69], v[188:191], v[230:233], 0
	v_mfma_f32_16x16x32_bf16 v[138:141], v[184:187], v[200:203], v[138:141]
	v_mfma_f32_16x16x32_bf16 v[130:133], v[192:195], v[200:203], v[130:133]
	v_mfma_f32_16x16x32_bf16 v[122:125], v[184:187], v[208:211], v[122:125]
	v_mfma_f32_16x16x32_bf16 v[114:117], v[192:195], v[208:211], v[114:117]
	v_mfma_f32_16x16x32_bf16 v[106:109], v[184:187], v[216:219], v[106:109]
	v_mfma_f32_16x16x32_bf16 v[98:101], v[192:195], v[216:219], v[98:101]
	v_mfma_f32_16x16x32_bf16 v[82:85], v[184:187], v[238:241], v[82:85]
	v_mfma_f32_16x16x32_bf16 v[66:69], v[192:195], v[238:241], v[66:69]
	s_setprio 0
	s_barrier
	s_add_i32 s83, s83, s37
	v_lshl_add_u64 v[168:169], s[56:57], 0, v[150:151]
	s_mov_b32 m0, s83
	ds_read_b128 v[196:199], v177 offset:16384
	ds_read_b128 v[200:203], v177 offset:17408
	ds_read_b128 v[204:207], v177 offset:18432
	ds_read_b128 v[208:211], v177 offset:19456
	ds_read_b128 v[212:215], v177 offset:20480
	ds_read_b128 v[216:219], v177 offset:21504
	ds_read_b128 v[230:233], v177 offset:22528
	ds_read_b128 v[238:241], v177 offset:23552
	global_load_lds_dwordx4 v[168:169], off
	s_add_i32 m0, s83, 0x2000
	s_add_u32 s84, s56, 0x40000
	v_lshl_add_u64 v[242:243], s[56:57], 0, v[146:147]
	s_addc_u32 s85, s57, 0
	s_add_i32 s0, s0, s37
	global_load_lds_dwordx4 v[242:243], off
	v_lshl_add_u64 v[244:245], s[84:85], 0, v[150:151]
	s_mov_b32 m0, s0
	v_lshl_add_u64 v[246:247], s[58:59], 0, v[148:149]
	global_load_lds_dwordx4 v[244:245], off
	v_lshl_add_u64 v[244:245], s[84:85], 0, v[146:147]
	s_add_i32 m0, s0, 0x2000
	s_nop 0
	global_load_lds_dwordx4 v[244:245], off
	v_lshl_add_u64 v[244:245], s[58:59], 0, v[152:153]
	s_mov_b32 m0, s61
	s_nop 0
	global_load_lds_dwordx4 v[244:245], off
	s_mov_b32 m0, s64
	s_nop 0
	global_load_lds_dwordx4 v[246:247], off
	s_waitcnt vmcnt(8)
	s_waitcnt lgkmcnt(0)
	s_barrier
	s_setprio 1
	s_waitcnt lgkmcnt(0)
	v_mfma_f32_16x16x32_bf16 v[62:65], v[74:77], v[196:199], 0
	v_mfma_f32_16x16x32_bf16 v[54:57], v[90:93], v[196:199], 0
	v_mfma_f32_16x16x32_bf16 v[46:49], v[74:77], v[204:207], 0
	v_mfma_f32_16x16x32_bf16 v[38:41], v[90:93], v[204:207], 0
	v_mfma_f32_16x16x32_bf16 v[30:33], v[74:77], v[212:215], 0
	v_mfma_f32_16x16x32_bf16 v[22:25], v[90:93], v[212:215], 0
	v_mfma_f32_16x16x32_bf16 v[14:17], v[74:77], v[230:233], 0
	v_mfma_f32_16x16x32_bf16 v[6:9], v[90:93], v[230:233], 0
	v_mfma_f32_16x16x32_bf16 v[62:65], v[78:81], v[200:203], v[62:65]
	v_mfma_f32_16x16x32_bf16 v[54:57], v[94:97], v[200:203], v[54:57]
	v_mfma_f32_16x16x32_bf16 v[46:49], v[78:81], v[208:211], v[46:49]
	v_mfma_f32_16x16x32_bf16 v[38:41], v[94:97], v[208:211], v[38:41]
	v_mfma_f32_16x16x32_bf16 v[30:33], v[78:81], v[216:219], v[30:33]
	v_mfma_f32_16x16x32_bf16 v[22:25], v[94:97], v[216:219], v[22:25]
	v_mfma_f32_16x16x32_bf16 v[14:17], v[78:81], v[238:241], v[14:17]
	v_mfma_f32_16x16x32_bf16 v[6:9], v[94:97], v[238:241], v[6:9]
	s_setprio 0
	s_setprio 1
	v_mfma_f32_16x16x32_bf16 v[58:61], v[180:183], v[196:199], 0
	v_mfma_f32_16x16x32_bf16 v[50:53], v[188:191], v[196:199], 0
	v_mfma_f32_16x16x32_bf16 v[42:45], v[180:183], v[204:207], 0
	v_mfma_f32_16x16x32_bf16 v[34:37], v[188:191], v[204:207], 0
	v_mfma_f32_16x16x32_bf16 v[26:29], v[180:183], v[212:215], 0
	v_mfma_f32_16x16x32_bf16 v[18:21], v[188:191], v[212:215], 0
	v_mfma_f32_16x16x32_bf16 v[10:13], v[180:183], v[230:233], 0
	v_mfma_f32_16x16x32_bf16 v[2:5], v[188:191], v[230:233], 0
	v_mfma_f32_16x16x32_bf16 v[58:61], v[184:187], v[200:203], v[58:61]
	v_mfma_f32_16x16x32_bf16 v[50:53], v[192:195], v[200:203], v[50:53]
	v_mfma_f32_16x16x32_bf16 v[42:45], v[184:187], v[208:211], v[42:45]
	v_mfma_f32_16x16x32_bf16 v[34:37], v[192:195], v[208:211], v[34:37]
	v_mfma_f32_16x16x32_bf16 v[26:29], v[184:187], v[216:219], v[26:29]
	v_mfma_f32_16x16x32_bf16 v[18:21], v[192:195], v[216:219], v[18:21]
	v_mfma_f32_16x16x32_bf16 v[10:13], v[184:187], v[238:241], v[10:13]
	v_mfma_f32_16x16x32_bf16 v[2:5], v[192:195], v[238:241], v[2:5]
	s_setprio 0
	s_barrier
	s_add_i32 s0, 0, 0x18000
	s_add_i32 s83, 0, 0x1c000
	v_add_u32_e32 v94, s0, v171
	v_add_u32_e32 v155, s83, v171
	ds_read_b128 v[74:77], v94
	ds_read_b128 v[78:81], v94 offset:1024
	ds_read_b128 v[90:93], v94 offset:2048
	ds_read_b128 v[94:97], v94 offset:3072
	ds_read_b128 v[180:183], v155
	ds_read_b128 v[184:187], v155 offset:1024
	ds_read_b128 v[188:191], v155 offset:2048
	ds_read_b128 v[192:195], v155 offset:3072
	s_add_u32 s58, s58, 0x40000
	s_addc_u32 s59, s59, 0
	s_mov_b32 m0, s65
	v_lshl_add_u64 v[248:249], s[58:59], 0, v[152:153]
	ds_read_b128 v[196:199], v177 offset:32768
	ds_read_b128 v[200:203], v177 offset:33792
	ds_read_b128 v[204:207], v177 offset:34816
	ds_read_b128 v[208:211], v177 offset:35840
	ds_read_b128 v[212:215], v177 offset:36864
	ds_read_b128 v[216:219], v177 offset:37888
	ds_read_b128 v[230:233], v177 offset:38912
	ds_read_b128 v[238:241], v177 offset:39936
	global_load_lds_dwordx4 v[248:249], off
	v_lshl_add_u64 v[248:249], s[58:59], 0, v[148:149]
	s_mov_b32 m0, s66
	s_nop 0
	global_load_lds_dwordx4 v[248:249], off
	s_waitcnt vmcnt(8)
	s_waitcnt lgkmcnt(0)
	s_barrier
	s_setprio 1
	s_waitcnt lgkmcnt(0)
	v_mfma_f32_16x16x32_bf16 v[142:145], v[74:77], v[196:199], v[142:145]
	v_mfma_f32_16x16x32_bf16 v[134:137], v[90:93], v[196:199], v[134:137]
	v_mfma_f32_16x16x32_bf16 v[126:129], v[74:77], v[204:207], v[126:129]
	v_mfma_f32_16x16x32_bf16 v[118:121], v[90:93], v[204:207], v[118:121]
	v_mfma_f32_16x16x32_bf16 v[110:113], v[74:77], v[212:215], v[110:113]
	v_mfma_f32_16x16x32_bf16 v[102:105], v[90:93], v[212:215], v[102:105]
	v_mfma_f32_16x16x32_bf16 v[86:89], v[74:77], v[230:233], v[86:89]
	v_mfma_f32_16x16x32_bf16 v[70:73], v[90:93], v[230:233], v[70:73]
	v_mfma_f32_16x16x32_bf16 v[142:145], v[78:81], v[200:203], v[142:145]
	v_mfma_f32_16x16x32_bf16 v[134:137], v[94:97], v[200:203], v[134:137]
	v_mfma_f32_16x16x32_bf16 v[126:129], v[78:81], v[208:211], v[126:129]
	v_mfma_f32_16x16x32_bf16 v[118:121], v[94:97], v[208:211], v[118:121]
	v_mfma_f32_16x16x32_bf16 v[110:113], v[78:81], v[216:219], v[110:113]
	v_mfma_f32_16x16x32_bf16 v[102:105], v[94:97], v[216:219], v[102:105]
	v_mfma_f32_16x16x32_bf16 v[86:89], v[78:81], v[238:241], v[86:89]
	v_mfma_f32_16x16x32_bf16 v[70:73], v[94:97], v[238:241], v[70:73]
	s_setprio 0
	s_setprio 1
	v_mfma_f32_16x16x32_bf16 v[138:141], v[180:183], v[196:199], v[138:141]
	v_mfma_f32_16x16x32_bf16 v[130:133], v[188:191], v[196:199], v[130:133]
	v_mfma_f32_16x16x32_bf16 v[122:125], v[180:183], v[204:207], v[122:125]
	v_mfma_f32_16x16x32_bf16 v[114:117], v[188:191], v[204:207], v[114:117]
	v_mfma_f32_16x16x32_bf16 v[106:109], v[180:183], v[212:215], v[106:109]
	v_mfma_f32_16x16x32_bf16 v[98:101], v[188:191], v[212:215], v[98:101]
	v_mfma_f32_16x16x32_bf16 v[82:85], v[180:183], v[230:233], v[82:85]
	v_mfma_f32_16x16x32_bf16 v[66:69], v[188:191], v[230:233], v[66:69]
	v_mfma_f32_16x16x32_bf16 v[138:141], v[184:187], v[200:203], v[138:141]
	v_mfma_f32_16x16x32_bf16 v[130:133], v[192:195], v[200:203], v[130:133]
	v_mfma_f32_16x16x32_bf16 v[122:125], v[184:187], v[208:211], v[122:125]
	v_mfma_f32_16x16x32_bf16 v[114:117], v[192:195], v[208:211], v[114:117]
	v_mfma_f32_16x16x32_bf16 v[106:109], v[184:187], v[216:219], v[106:109]
	v_mfma_f32_16x16x32_bf16 v[98:101], v[192:195], v[216:219], v[98:101]
	v_mfma_f32_16x16x32_bf16 v[82:85], v[184:187], v[238:241], v[82:85]
	v_mfma_f32_16x16x32_bf16 v[66:69], v[192:195], v[238:241], v[66:69]
	s_setprio 0
	s_barrier
	s_add_i32 s0, s0, s37
	v_lshl_add_u64 v[168:169], v[168:169], 0, s[76:77]
	s_mov_b32 m0, s0
	ds_read_b128 v[196:199], v177 offset:49152
	ds_read_b128 v[200:203], v177 offset:50176
	ds_read_b128 v[204:207], v177 offset:51200
	ds_read_b128 v[208:211], v177 offset:52224
	ds_read_b128 v[212:215], v177 offset:53248
	ds_read_b128 v[216:219], v177 offset:54272
	ds_read_b128 v[230:233], v177 offset:55296
	ds_read_b128 v[238:241], v177 offset:56320
	global_load_lds_dwordx4 v[168:169], off
	s_add_i32 m0, s0, 0x2000
	s_add_u32 s56, s56, 0x40080
	v_lshl_add_u64 v[168:169], v[242:243], 0, s[76:77]
	s_addc_u32 s57, s57, 0
	s_add_i32 s0, s83, s37
	global_load_lds_dwordx4 v[168:169], off
	v_lshl_add_u64 v[168:169], s[56:57], 0, v[150:151]
	s_mov_b32 m0, s0
	s_nop 0
	global_load_lds_dwordx4 v[168:169], off
	v_lshl_add_u64 v[168:169], s[56:57], 0, v[146:147]
	s_add_i32 m0, s0, 0x2000
	s_nop 0
	global_load_lds_dwordx4 v[168:169], off
	v_lshl_add_u64 v[168:169], v[244:245], 0, s[76:77]
	s_mov_b32 m0, s67
	s_nop 0
	global_load_lds_dwordx4 v[168:169], off
	v_lshl_add_u64 v[168:169], v[246:247], 0, s[76:77]
	s_mov_b32 m0, s68
	s_nop 0
	global_load_lds_dwordx4 v[168:169], off
	s_waitcnt vmcnt(8)
	s_waitcnt lgkmcnt(0)
	s_barrier
	s_setprio 1
	s_waitcnt lgkmcnt(0)
	v_mfma_f32_16x16x32_bf16 v[62:65], v[74:77], v[196:199], v[62:65]
	v_mfma_f32_16x16x32_bf16 v[54:57], v[90:93], v[196:199], v[54:57]
	v_mfma_f32_16x16x32_bf16 v[46:49], v[74:77], v[204:207], v[46:49]
	v_mfma_f32_16x16x32_bf16 v[38:41], v[90:93], v[204:207], v[38:41]
	v_mfma_f32_16x16x32_bf16 v[30:33], v[74:77], v[212:215], v[30:33]
	v_mfma_f32_16x16x32_bf16 v[22:25], v[90:93], v[212:215], v[22:25]
	v_mfma_f32_16x16x32_bf16 v[14:17], v[74:77], v[230:233], v[14:17]
	v_mfma_f32_16x16x32_bf16 v[6:9], v[90:93], v[230:233], v[6:9]
	v_mfma_f32_16x16x32_bf16 v[62:65], v[78:81], v[200:203], v[62:65]
	v_mfma_f32_16x16x32_bf16 v[54:57], v[94:97], v[200:203], v[54:57]
	v_mfma_f32_16x16x32_bf16 v[46:49], v[78:81], v[208:211], v[46:49]
	v_mfma_f32_16x16x32_bf16 v[38:41], v[94:97], v[208:211], v[38:41]
	v_mfma_f32_16x16x32_bf16 v[30:33], v[78:81], v[216:219], v[30:33]
	v_mfma_f32_16x16x32_bf16 v[22:25], v[94:97], v[216:219], v[22:25]
	v_mfma_f32_16x16x32_bf16 v[14:17], v[78:81], v[238:241], v[14:17]
	v_mfma_f32_16x16x32_bf16 v[6:9], v[94:97], v[238:241], v[6:9]
	s_setprio 0
	s_setprio 1
	v_mfma_f32_16x16x32_bf16 v[58:61], v[180:183], v[196:199], v[58:61]
	v_mfma_f32_16x16x32_bf16 v[50:53], v[188:191], v[196:199], v[50:53]
	v_mfma_f32_16x16x32_bf16 v[42:45], v[180:183], v[204:207], v[42:45]
	v_mfma_f32_16x16x32_bf16 v[34:37], v[188:191], v[204:207], v[34:37]
	v_mfma_f32_16x16x32_bf16 v[26:29], v[180:183], v[212:215], v[26:29]
	v_mfma_f32_16x16x32_bf16 v[18:21], v[188:191], v[212:215], v[18:21]
	v_mfma_f32_16x16x32_bf16 v[10:13], v[180:183], v[230:233], v[10:13]
	v_mfma_f32_16x16x32_bf16 v[2:5], v[188:191], v[230:233], v[2:5]
	v_mfma_f32_16x16x32_bf16 v[58:61], v[184:187], v[200:203], v[58:61]
	v_mfma_f32_16x16x32_bf16 v[50:53], v[192:195], v[200:203], v[50:53]
	v_mfma_f32_16x16x32_bf16 v[42:45], v[184:187], v[208:211], v[42:45]
	v_mfma_f32_16x16x32_bf16 v[34:37], v[192:195], v[208:211], v[34:37]
	v_mfma_f32_16x16x32_bf16 v[26:29], v[184:187], v[216:219], v[26:29]
	v_mfma_f32_16x16x32_bf16 v[18:21], v[192:195], v[216:219], v[18:21]
	v_mfma_f32_16x16x32_bf16 v[10:13], v[184:187], v[238:241], v[10:13]
	v_mfma_f32_16x16x32_bf16 v[2:5], v[192:195], v[238:241], v[2:5]
	s_setprio 0
	s_barrier
	s_add_i32 s82, s82, 2
	s_add_u32 s52, s52, 0x100
	s_addc_u32 s53, s53, 0
	s_add_u32 s73, s73, 0x100
	s_addc_u32 s75, s75, 0
	.p2align	6

.LBB0_267:
	v_or_b32_e32 v82, s8, v1
	v_and_b32_e32 v66, 63, v16
	v_lshlrev_b32_e32 v3, 6, v82
	s_movk_i32 s0, 0x3c0
	v_lshlrev_b32_e32 v16, 2, v82
	v_and_or_b32 v3, v3, s0, v18
	s_lshl_b32 s0, s3, 13
	v_and_b32_e32 v16, 32, v16
	v_bitop3_b32 v16, v3, s0, v16 bitop3:0xde
	v_lshl_or_b32 v3, v1, 6, v18
	s_lshl_b32 s0, s14, 12
	v_and_b32_e32 v2, 32, v2
	v_bitop3_b32 v67, v3, s0, v2 bitop3:0xde
	s_add_i32 m0, s35, 0x18000
	v_lshl_add_u64 v[2:3], v[10:11], 0, s[76:77]
	s_lshl_b32 s21, s14, 5
	s_waitcnt vmcnt(2)
	s_barrier
	global_load_lds_dwordx4 v[2:3], off
	v_lshl_add_u64 v[2:3], v[8:9], 0, s[76:77]
	s_add_i32 m0, s35, 0x1a000
	s_add_i32 s37, s35, 0x8000
	s_add_i32 s38, s35, 0xa000
	global_load_lds_dwordx4 v[2:3], off
	v_lshl_add_u64 v[2:3], v[6:7], 0, s[76:77]
	s_mov_b32 m0, s37
	s_add_u32 s8, s4, 0x40080
	global_load_lds_dwordx4 v[2:3], off
	v_lshl_add_u64 v[2:3], v[4:5], 0, s[76:77]
	s_mov_b32 m0, s38
	s_addc_u32 s9, s5, 0
	global_load_lds_dwordx4 v[2:3], off
	s_add_i32 m0, s35, 0x1c000
	v_lshl_add_u64 v[2:3], s[8:9], 0, v[50:51]
	global_load_lds_dwordx4 v[2:3], off
	v_lshl_add_u64 v[2:3], s[8:9], 0, v[46:47]
	s_add_i32 m0, s35, 0x1e000
	v_readlane_b32 s0, v254, 53
	global_load_lds_dwordx4 v[2:3], off
	v_lshlrev_b32_e32 v2, 14, v12
	v_and_b32_e32 v2, 0xffff8000, v2
	v_lshl_add_u32 v2, v13, 11, v2
	v_and_b32_e32 v3, 1, v12
	s_add_u32 s8, s26, s0
	v_lshl_or_b32 v2, v3, 6, v2
	s_addc_u32 s9, s1, 0
	v_lshl_add_u32 v2, v14, 1, v2
	v_mov_b32_e32 v3, v0
	v_lshl_add_u64 v[62:63], s[8:9], 0, v[2:3]
	v_lshlrev_b32_e32 v2, 14, v17
	v_and_b32_e32 v2, 0xffff8000, v2
	v_lshl_add_u32 v2, v15, 11, v2
	v_and_b32_e32 v3, 1, v17
	v_readlane_b32 s0, v254, 52
	v_lshl_or_b32 v2, v3, 6, v2
	s_add_u32 s40, s26, s0
	v_lshl_add_u32 v2, v19, 1, v2
	v_mov_b32_e32 v3, v0
	s_addc_u32 s41, s1, 0
	v_readlane_b32 s0, v254, 54
	v_lshl_add_u64 v[64:65], s[8:9], 0, v[2:3]
	s_add_u32 s0, s26, s0
	v_readlane_b32 s8, v254, 55
	s_addc_u32 s8, s1, s8
	s_add_u32 s1, s27, s30
	s_waitcnt vmcnt(6)
	s_addc_u32 s9, 0, 0
	s_add_u32 s1, s0, s1
	s_addc_u32 s26, s8, s9
	s_mov_b32 s27, -2
	s_mov_b64 s[8:9], 0
	v_add_u32_e32 v68, 0, v16
	s_barrier
	s_add_u32 s0, s40, s8
	s_addc_u32 s10, s41, s9
	s_add_u32 s0, s0, 0x7c00100
	s_addc_u32 s10, s10, 0
	s_add_u32 s30, s1, s8
	s_addc_u32 s11, s26, s9
	s_add_i32 s42, 0, 0x10000
	s_cmpk_eq_i32 s8, 0x700
	s_cselect_b32 s13, s7, s10
	s_cselect_b32 s12, s6, s0
	v_add_u32_e32 v69, s42, v67
	s_cselect_b32 s11, s5, s11
	s_cselect_b32 s10, s4, s30
	s_add_i32 s0, 0, 0x14000
	ds_read_b128 v[84:87], v69
	ds_read_b128 v[88:91], v69 offset:1024
	ds_read_b128 v[92:95], v69 offset:2048
	ds_read_b128 v[96:99], v69 offset:3072
	v_add_u32_e32 v69, s0, v67
	ds_read_b128 v[100:103], v69
	ds_read_b128 v[104:107], v69 offset:1024
	ds_read_b128 v[108:111], v69 offset:2048
	ds_read_b128 v[112:115], v69 offset:3072
	v_lshl_add_u64 v[148:149], v[64:65], 0, s[8:9]
	s_add_i32 m0, s35, 0xc000
	ds_read_b128 v[116:119], v68
	ds_read_b128 v[120:123], v68 offset:1024
	ds_read_b128 v[124:127], v68 offset:2048
	ds_read_b128 v[128:131], v68 offset:3072
	ds_read_b128 v[132:135], v68 offset:4096
	ds_read_b128 v[136:139], v68 offset:5120
	ds_read_b128 v[140:143], v68 offset:6144
	ds_read_b128 v[144:147], v68 offset:7168
	global_load_lds_dwordx4 v[148:149], off
	v_lshl_add_u64 v[148:149], v[62:63], 0, s[8:9]
	s_add_i32 m0, s35, 0xe000
	s_nop 0
	global_load_lds_dwordx4 v[148:149], off
	s_waitcnt vmcnt(8)
	s_waitcnt lgkmcnt(0)
	s_barrier
	s_setprio 1
	s_waitcnt lgkmcnt(0)
	v_mfma_f32_16x16x32_bf16 v[78:81], v[84:87], v[116:119], 0
	v_mfma_f32_16x16x32_bf16 v[70:73], v[92:95], v[116:119], 0
	v_mfma_f32_16x16x32_bf16 v[54:57], v[84:87], v[124:127], 0
	v_mfma_f32_16x16x32_bf16 v[38:41], v[92:95], v[124:127], 0
	v_mfma_f32_16x16x32_bf16 v[30:33], v[84:87], v[132:135], 0
	v_mfma_f32_16x16x32_bf16 v[22:25], v[92:95], v[132:135], 0
	v_mfma_f32_16x16x32_bf16 v[14:17], v[84:87], v[140:143], 0
	v_mfma_f32_16x16x32_bf16 v[6:9], v[92:95], v[140:143], 0
	v_mfma_f32_16x16x32_bf16 v[78:81], v[88:91], v[120:123], v[78:81]
	v_mfma_f32_16x16x32_bf16 v[70:73], v[96:99], v[120:123], v[70:73]
	v_mfma_f32_16x16x32_bf16 v[54:57], v[88:91], v[128:131], v[54:57]
	v_mfma_f32_16x16x32_bf16 v[38:41], v[96:99], v[128:131], v[38:41]
	v_mfma_f32_16x16x32_bf16 v[30:33], v[88:91], v[136:139], v[30:33]
	v_mfma_f32_16x16x32_bf16 v[22:25], v[96:99], v[136:139], v[22:25]
	v_mfma_f32_16x16x32_bf16 v[14:17], v[88:91], v[144:147], v[14:17]
	v_mfma_f32_16x16x32_bf16 v[6:9], v[96:99], v[144:147], v[6:9]
	s_setprio 0
	s_setprio 1
	v_mfma_f32_16x16x32_bf16 v[74:77], v[100:103], v[116:119], 0
	v_mfma_f32_16x16x32_bf16 v[58:61], v[108:111], v[116:119], 0
	v_mfma_f32_16x16x32_bf16 v[42:45], v[100:103], v[124:127], 0
	v_mfma_f32_16x16x32_bf16 v[34:37], v[108:111], v[124:127], 0
	v_mfma_f32_16x16x32_bf16 v[26:29], v[100:103], v[132:135], 0
	v_mfma_f32_16x16x32_bf16 v[18:21], v[108:111], v[132:135], 0
	v_mfma_f32_16x16x32_bf16 v[10:13], v[100:103], v[140:143], 0
	v_mfma_f32_16x16x32_bf16 v[2:5], v[108:111], v[140:143], 0
	v_mfma_f32_16x16x32_bf16 v[74:77], v[104:107], v[120:123], v[74:77]
	v_mfma_f32_16x16x32_bf16 v[58:61], v[112:115], v[120:123], v[58:61]
	v_mfma_f32_16x16x32_bf16 v[42:45], v[104:107], v[128:131], v[42:45]
	v_mfma_f32_16x16x32_bf16 v[34:37], v[112:115], v[128:131], v[34:37]
	v_mfma_f32_16x16x32_bf16 v[26:29], v[104:107], v[136:139], v[26:29]
	v_mfma_f32_16x16x32_bf16 v[18:21], v[112:115], v[136:139], v[18:21]
	v_mfma_f32_16x16x32_bf16 v[10:13], v[104:107], v[144:147], v[10:13]
	v_mfma_f32_16x16x32_bf16 v[2:5], v[112:115], v[144:147], v[2:5]
	s_setprio 0
	s_barrier
	s_add_i32 s30, s42, s20
	v_lshl_add_u64 v[148:149], s[10:11], 0, v[50:51]
	s_mov_b32 m0, s30
	v_lshl_add_u64 v[150:151], s[10:11], 0, v[46:47]
	global_load_lds_dwordx4 v[148:149], off
	s_add_i32 m0, s30, 0x2000
	s_add_u32 s42, s10, 0x40000
	s_addc_u32 s43, s11, 0
	s_add_i32 s0, s0, s20
	global_load_lds_dwordx4 v[150:151], off
	v_lshl_add_u64 v[84:85], s[42:43], 0, v[50:51]
	s_mov_b32 m0, s0
	v_lshl_add_u64 v[152:153], s[12:13], 0, v[52:53]
	global_load_lds_dwordx4 v[84:85], off
	v_lshl_add_u64 v[84:85], s[42:43], 0, v[46:47]
	s_add_i32 m0, s0, 0x2000
	v_lshl_add_u64 v[154:155], s[12:13], 0, v[48:49]
	global_load_lds_dwordx4 v[84:85], off
	s_mov_b32 m0, s35
	s_nop 0
	global_load_lds_dwordx4 v[152:153], off
	s_mov_b32 m0, s31
	s_nop 0
	global_load_lds_dwordx4 v[154:155], off
	s_waitcnt vmcnt(8)
	s_waitcnt lgkmcnt(0)
	s_barrier
	s_barrier
	s_add_i32 s0, 0, 0x18000
	v_add_u32_e32 v69, s0, v67
	s_add_i32 s12, 0, 0x1c000
	ds_read_b128 v[84:87], v69
	ds_read_b128 v[88:91], v69 offset:1024
	ds_read_b128 v[92:95], v69 offset:2048
	ds_read_b128 v[96:99], v69 offset:3072
	v_add_u32_e32 v69, s12, v67
	ds_read_b128 v[100:103], v69
	ds_read_b128 v[104:107], v69 offset:1024
	ds_read_b128 v[108:111], v69 offset:2048
	ds_read_b128 v[112:115], v69 offset:3072
	s_mov_b32 m0, s34
	ds_read_b128 v[116:119], v68 offset:32768
	ds_read_b128 v[120:123], v68 offset:33792
	ds_read_b128 v[124:127], v68 offset:34816
	ds_read_b128 v[128:131], v68 offset:35840
	ds_read_b128 v[132:135], v68 offset:36864
	ds_read_b128 v[136:139], v68 offset:37888
	ds_read_b128 v[140:143], v68 offset:38912
	ds_read_b128 v[144:147], v68 offset:39936
	global_load_lds_dwordx4 v[152:153], off
	s_mov_b32 m0, s36
	s_nop 0
	global_load_lds_dwordx4 v[154:155], off
	s_waitcnt vmcnt(8)
	s_waitcnt lgkmcnt(0)
	s_barrier
	s_setprio 1
	s_waitcnt lgkmcnt(0)
	v_mfma_f32_16x16x32_bf16 v[78:81], v[84:87], v[116:119], v[78:81]
	v_mfma_f32_16x16x32_bf16 v[70:73], v[92:95], v[116:119], v[70:73]
	v_mfma_f32_16x16x32_bf16 v[54:57], v[84:87], v[124:127], v[54:57]
	v_mfma_f32_16x16x32_bf16 v[38:41], v[92:95], v[124:127], v[38:41]
	v_mfma_f32_16x16x32_bf16 v[30:33], v[84:87], v[132:135], v[30:33]
	v_mfma_f32_16x16x32_bf16 v[22:25], v[92:95], v[132:135], v[22:25]
	v_mfma_f32_16x16x32_bf16 v[14:17], v[84:87], v[140:143], v[14:17]
	v_mfma_f32_16x16x32_bf16 v[6:9], v[92:95], v[140:143], v[6:9]
	v_mfma_f32_16x16x32_bf16 v[78:81], v[88:91], v[120:123], v[78:81]
	v_mfma_f32_16x16x32_bf16 v[70:73], v[96:99], v[120:123], v[70:73]
	v_mfma_f32_16x16x32_bf16 v[54:57], v[88:91], v[128:131], v[54:57]
	v_mfma_f32_16x16x32_bf16 v[38:41], v[96:99], v[128:131], v[38:41]
	v_mfma_f32_16x16x32_bf16 v[30:33], v[88:91], v[136:139], v[30:33]
	v_mfma_f32_16x16x32_bf16 v[22:25], v[96:99], v[136:139], v[22:25]
	v_mfma_f32_16x16x32_bf16 v[14:17], v[88:91], v[144:147], v[14:17]
	v_mfma_f32_16x16x32_bf16 v[6:9], v[96:99], v[144:147], v[6:9]
	s_setprio 0
	s_setprio 1
	v_mfma_f32_16x16x32_bf16 v[74:77], v[100:103], v[116:119], v[74:77]
	v_mfma_f32_16x16x32_bf16 v[58:61], v[108:111], v[116:119], v[58:61]
	v_mfma_f32_16x16x32_bf16 v[42:45], v[100:103], v[124:127], v[42:45]
	v_mfma_f32_16x16x32_bf16 v[34:37], v[108:111], v[124:127], v[34:37]
	v_mfma_f32_16x16x32_bf16 v[26:29], v[100:103], v[132:135], v[26:29]
	v_mfma_f32_16x16x32_bf16 v[18:21], v[108:111], v[132:135], v[18:21]
	v_mfma_f32_16x16x32_bf16 v[10:13], v[100:103], v[140:143], v[10:13]
	v_mfma_f32_16x16x32_bf16 v[2:5], v[108:111], v[140:143], v[2:5]
	v_mfma_f32_16x16x32_bf16 v[74:77], v[104:107], v[120:123], v[74:77]
	v_mfma_f32_16x16x32_bf16 v[58:61], v[112:115], v[120:123], v[58:61]
	v_mfma_f32_16x16x32_bf16 v[42:45], v[104:107], v[128:131], v[42:45]
	v_mfma_f32_16x16x32_bf16 v[34:37], v[112:115], v[128:131], v[34:37]
	v_mfma_f32_16x16x32_bf16 v[26:29], v[104:107], v[136:139], v[26:29]
	v_mfma_f32_16x16x32_bf16 v[18:21], v[112:115], v[136:139], v[18:21]
	v_mfma_f32_16x16x32_bf16 v[10:13], v[104:107], v[144:147], v[10:13]
	v_mfma_f32_16x16x32_bf16 v[2:5], v[112:115], v[144:147], v[2:5]
	s_setprio 0
	s_barrier
	s_add_i32 s0, s0, s20
	v_lshl_add_u64 v[84:85], v[148:149], 0, s[76:77]
	s_mov_b32 m0, s0
	s_nop 0
	global_load_lds_dwordx4 v[84:85], off
	s_add_i32 m0, s0, 0x2000
	s_add_u32 s10, s10, 0x40080
	v_lshl_add_u64 v[84:85], v[150:151], 0, s[76:77]
	s_addc_u32 s11, s11, 0
	s_add_i32 s0, s12, s20
	global_load_lds_dwordx4 v[84:85], off
	v_lshl_add_u64 v[84:85], s[10:11], 0, v[50:51]
	s_mov_b32 m0, s0
	s_nop 0
	global_load_lds_dwordx4 v[84:85], off
	v_lshl_add_u64 v[84:85], s[10:11], 0, v[46:47]
	s_add_i32 m0, s0, 0x2000
	s_nop 0
	global_load_lds_dwordx4 v[84:85], off
	v_lshl_add_u64 v[84:85], v[152:153], 0, s[76:77]
	s_mov_b32 m0, s37
	s_nop 0
	global_load_lds_dwordx4 v[84:85], off
	v_lshl_add_u64 v[84:85], v[154:155], 0, s[76:77]
	s_mov_b32 m0, s38
	s_nop 0
	global_load_lds_dwordx4 v[84:85], off
	s_waitcnt vmcnt(8)
	s_waitcnt lgkmcnt(0)
	s_barrier
	s_barrier
	s_add_i32 s27, s27, 2
	s_add_u32 s8, s8, 0x100
	s_addc_u32 s9, s9, 0
	.p2align	6

.LBB0_282:
	s_ashr_i32 s59, s58, 31
	s_lshl_b64 s[20:21], s[58:59], 19
	s_add_u32 s64, s26, s20
	s_addc_u32 s65, s27, s21
	s_and_b64 s[20:21], s[8:9], exec
	s_cselect_b32 s20, s65, s5
	s_cselect_b32 s21, s64, s4
	s_ashr_i32 s57, s56, 31
	s_lshl_b64 s[36:37], s[56:57], 19
	s_add_u32 s66, s35, s36
	s_addc_u32 s67, s40, s37
	s_and_b64 s[36:37], s[8:9], exec
	s_cselect_b32 s36, s67, s7
	s_cselect_b32 s37, s66, s6
	s_add_u32 s4, s4, 0x40080
	s_addc_u32 s5, s5, 0
	s_add_u32 s46, s6, 0x100
	s_addc_u32 s57, s7, 0
	s_mov_b32 s59, -2
	s_add_u32 s6, s4, 0xfffc0080
	s_addc_u32 s7, s5, -1
	s_add_i32 s82, 0, 0x10000
	s_cmp_eq_u32 s59, 12
	s_cselect_b32 s69, s20, s7
	s_cselect_b32 s68, s21, s6
	s_cselect_b32 s7, s36, s57
	s_cselect_b32 s6, s37, s46
	s_add_i32 s84, 0, 0x14000
	v_add_u32_e32 v142, s82, v202
	v_add_u32_e32 v158, s84, v202
	ds_read_b128 v[130:133], v142
	ds_read_b128 v[134:137], v142 offset:1024
	ds_read_b128 v[138:141], v142 offset:2048
	ds_read_b128 v[142:145], v142 offset:3072
	ds_read_b128 v[146:149], v158
	ds_read_b128 v[150:153], v158 offset:1024
	ds_read_b128 v[154:157], v158 offset:2048
	ds_read_b128 v[158:161], v158 offset:3072
	v_lshl_add_u64 v[218:219], s[4:5], 0, v[182:183]
	s_add_i32 m0, s87, 0xc000
	ds_read_b128 v[186:189], v204
	ds_read_b128 v[190:193], v204 offset:1024
	ds_read_b128 v[194:197], v204 offset:2048
	ds_read_b128 v[198:201], v204 offset:3072
	ds_read_b128 v[206:209], v204 offset:4096
	ds_read_b128 v[210:213], v204 offset:5120
	ds_read_b128 v[214:217], v204 offset:6144
	ds_read_b128 v[238:241], v204 offset:7168
	global_load_lds_dwordx4 v[218:219], off
	v_lshl_add_u64 v[218:219], s[4:5], 0, v[184:185]
	s_add_i32 m0, s87, 0xe000
	s_nop 0
	global_load_lds_dwordx4 v[218:219], off
	s_waitcnt vmcnt(8)
	s_waitcnt lgkmcnt(0)
	s_barrier
	s_setprio 1
	s_waitcnt lgkmcnt(0)
	v_mfma_f32_16x16x32_bf16 v[2:5], v[130:133], v[186:189], 0
	v_mfma_f32_16x16x32_bf16 v[6:9], v[138:141], v[186:189], 0
	v_mfma_f32_16x16x32_bf16 v[30:33], v[130:133], v[194:197], 0
	v_mfma_f32_16x16x32_bf16 v[26:29], v[138:141], v[194:197], 0
	v_mfma_f32_16x16x32_bf16 v[34:37], v[130:133], v[206:209], 0
	v_mfma_f32_16x16x32_bf16 v[42:45], v[138:141], v[206:209], 0
	v_mfma_f32_16x16x32_bf16 v[62:65], v[130:133], v[214:217], 0
	v_mfma_f32_16x16x32_bf16 v[58:61], v[138:141], v[214:217], 0
	v_mfma_f32_16x16x32_bf16 v[2:5], v[134:137], v[190:193], v[2:5]
	v_mfma_f32_16x16x32_bf16 v[6:9], v[142:145], v[190:193], v[6:9]
	v_mfma_f32_16x16x32_bf16 v[30:33], v[134:137], v[198:201], v[30:33]
	v_mfma_f32_16x16x32_bf16 v[26:29], v[142:145], v[198:201], v[26:29]
	v_mfma_f32_16x16x32_bf16 v[34:37], v[134:137], v[210:213], v[34:37]
	v_mfma_f32_16x16x32_bf16 v[42:45], v[142:145], v[210:213], v[42:45]
	v_mfma_f32_16x16x32_bf16 v[62:65], v[134:137], v[238:241], v[62:65]
	v_mfma_f32_16x16x32_bf16 v[58:61], v[142:145], v[238:241], v[58:61]
	s_setprio 0
	s_setprio 1
	v_mfma_f32_16x16x32_bf16 v[14:17], v[146:149], v[186:189], 0
	v_mfma_f32_16x16x32_bf16 v[10:13], v[154:157], v[186:189], 0
	v_mfma_f32_16x16x32_bf16 v[22:25], v[146:149], v[194:197], 0
	v_mfma_f32_16x16x32_bf16 v[18:21], v[154:157], v[194:197], 0
	v_mfma_f32_16x16x32_bf16 v[46:49], v[146:149], v[206:209], 0
	v_mfma_f32_16x16x32_bf16 v[38:41], v[154:157], v[206:209], 0
	v_mfma_f32_16x16x32_bf16 v[54:57], v[146:149], v[214:217], 0
	v_mfma_f32_16x16x32_bf16 v[50:53], v[154:157], v[214:217], 0
	v_mfma_f32_16x16x32_bf16 v[14:17], v[150:153], v[190:193], v[14:17]
	v_mfma_f32_16x16x32_bf16 v[10:13], v[158:161], v[190:193], v[10:13]
	v_mfma_f32_16x16x32_bf16 v[22:25], v[150:153], v[198:201], v[22:25]
	v_mfma_f32_16x16x32_bf16 v[18:21], v[158:161], v[198:201], v[18:21]
	v_mfma_f32_16x16x32_bf16 v[46:49], v[150:153], v[210:213], v[46:49]
	v_mfma_f32_16x16x32_bf16 v[38:41], v[158:161], v[210:213], v[38:41]
	v_mfma_f32_16x16x32_bf16 v[54:57], v[150:153], v[238:241], v[54:57]
	v_mfma_f32_16x16x32_bf16 v[50:53], v[158:161], v[238:241], v[50:53]
	s_setprio 0
	s_barrier
	s_add_i32 s82, s82, s41
	v_lshl_add_u64 v[218:219], s[6:7], 0, v[164:165]
	s_mov_b32 m0, s82
	ds_read_b128 v[186:189], v204 offset:16384
	ds_read_b128 v[190:193], v204 offset:17408
	ds_read_b128 v[194:197], v204 offset:18432
	ds_read_b128 v[198:201], v204 offset:19456
	ds_read_b128 v[206:209], v204 offset:20480
	ds_read_b128 v[210:213], v204 offset:21504
	ds_read_b128 v[214:217], v204 offset:22528
	ds_read_b128 v[238:241], v204 offset:23552
	global_load_lds_dwordx4 v[218:219], off
	s_add_i32 m0, s82, 0x2000
	s_add_u32 s82, s6, 0x40000
	v_lshl_add_u64 v[230:231], s[6:7], 0, v[162:163]
	s_addc_u32 s83, s7, 0
	s_add_i32 s84, s84, s41
	global_load_lds_dwordx4 v[230:231], off
	v_lshl_add_u64 v[232:233], s[82:83], 0, v[164:165]
	s_mov_b32 m0, s84
	v_lshl_add_u64 v[242:243], s[68:69], 0, v[162:163]
	global_load_lds_dwordx4 v[232:233], off
	v_lshl_add_u64 v[232:233], s[82:83], 0, v[162:163]
	s_add_i32 m0, s84, 0x2000
	s_nop 0
	global_load_lds_dwordx4 v[232:233], off
	v_lshl_add_u64 v[232:233], s[68:69], 0, v[164:165]
	s_mov_b32 m0, s87
	s_nop 0
	global_load_lds_dwordx4 v[232:233], off
	s_mov_b32 m0, s75
	s_nop 0
	global_load_lds_dwordx4 v[242:243], off
	s_waitcnt vmcnt(8)
	s_waitcnt lgkmcnt(0)
	s_barrier
	s_setprio 1
	s_waitcnt lgkmcnt(0)
	v_mfma_f32_16x16x32_bf16 v[74:77], v[130:133], v[186:189], 0
	v_mfma_f32_16x16x32_bf16 v[70:73], v[138:141], v[186:189], 0
	v_mfma_f32_16x16x32_bf16 v[94:97], v[130:133], v[194:197], 0
	v_mfma_f32_16x16x32_bf16 v[90:93], v[138:141], v[194:197], 0
	v_mfma_f32_16x16x32_bf16 v[106:109], v[130:133], v[206:209], 0
	v_mfma_f32_16x16x32_bf16 v[102:105], v[138:141], v[206:209], 0
	v_mfma_f32_16x16x32_bf16 v[118:121], v[130:133], v[214:217], 0
	v_mfma_f32_16x16x32_bf16 v[114:117], v[138:141], v[214:217], 0
	v_mfma_f32_16x16x32_bf16 v[74:77], v[134:137], v[190:193], v[74:77]
	v_mfma_f32_16x16x32_bf16 v[70:73], v[142:145], v[190:193], v[70:73]
	v_mfma_f32_16x16x32_bf16 v[94:97], v[134:137], v[198:201], v[94:97]
	v_mfma_f32_16x16x32_bf16 v[90:93], v[142:145], v[198:201], v[90:93]
	v_mfma_f32_16x16x32_bf16 v[106:109], v[134:137], v[210:213], v[106:109]
	v_mfma_f32_16x16x32_bf16 v[102:105], v[142:145], v[210:213], v[102:105]
	v_mfma_f32_16x16x32_bf16 v[118:121], v[134:137], v[238:241], v[118:121]
	v_mfma_f32_16x16x32_bf16 v[114:117], v[142:145], v[238:241], v[114:117]
	s_setprio 0
	s_setprio 1
	v_mfma_f32_16x16x32_bf16 v[78:81], v[146:149], v[186:189], 0
	v_mfma_f32_16x16x32_bf16 v[66:69], v[154:157], v[186:189], 0
	v_mfma_f32_16x16x32_bf16 v[86:89], v[146:149], v[194:197], 0
	v_mfma_f32_16x16x32_bf16 v[82:85], v[154:157], v[194:197], 0
	v_mfma_f32_16x16x32_bf16 v[110:113], v[146:149], v[206:209], 0
	v_mfma_f32_16x16x32_bf16 v[98:101], v[154:157], v[206:209], 0
	v_mfma_f32_16x16x32_bf16 v[122:125], v[146:149], v[214:217], 0
	v_mfma_f32_16x16x32_bf16 v[126:129], v[154:157], v[214:217], 0
	v_mfma_f32_16x16x32_bf16 v[78:81], v[150:153], v[190:193], v[78:81]
	v_mfma_f32_16x16x32_bf16 v[66:69], v[158:161], v[190:193], v[66:69]
	v_mfma_f32_16x16x32_bf16 v[86:89], v[150:153], v[198:201], v[86:89]
	v_mfma_f32_16x16x32_bf16 v[82:85], v[158:161], v[198:201], v[82:85]
	v_mfma_f32_16x16x32_bf16 v[110:113], v[150:153], v[210:213], v[110:113]
	v_mfma_f32_16x16x32_bf16 v[98:101], v[158:161], v[210:213], v[98:101]
	v_mfma_f32_16x16x32_bf16 v[122:125], v[150:153], v[238:241], v[122:125]
	v_mfma_f32_16x16x32_bf16 v[126:129], v[158:161], v[238:241], v[126:129]
	s_setprio 0
	s_barrier
	s_add_i32 s82, 0, 0x18000
	s_add_i32 s83, 0, 0x1c000
	v_add_u32_e32 v142, s82, v202
	v_add_u32_e32 v158, s83, v202
	ds_read_b128 v[130:133], v142
	ds_read_b128 v[134:137], v142 offset:1024
	ds_read_b128 v[138:141], v142 offset:2048
	ds_read_b128 v[142:145], v142 offset:3072
	ds_read_b128 v[146:149], v158
	ds_read_b128 v[150:153], v158 offset:1024
	ds_read_b128 v[154:157], v158 offset:2048
	ds_read_b128 v[158:161], v158 offset:3072
	s_add_u32 s68, s68, 0x40000
	s_addc_u32 s69, s69, 0
	s_mov_b32 m0, s72
	v_lshl_add_u64 v[244:245], s[68:69], 0, v[164:165]
	ds_read_b128 v[186:189], v204 offset:32768
	ds_read_b128 v[190:193], v204 offset:33792
	ds_read_b128 v[194:197], v204 offset:34816
	ds_read_b128 v[198:201], v204 offset:35840
	ds_read_b128 v[206:209], v204 offset:36864
	ds_read_b128 v[210:213], v204 offset:37888
	ds_read_b128 v[214:217], v204 offset:38912
	ds_read_b128 v[238:241], v204 offset:39936
	global_load_lds_dwordx4 v[244:245], off
	v_lshl_add_u64 v[244:245], s[68:69], 0, v[162:163]
	s_mov_b32 m0, s73
	s_nop 0
	global_load_lds_dwordx4 v[244:245], off
	s_waitcnt vmcnt(8)
	s_waitcnt lgkmcnt(0)
	s_barrier
	s_setprio 1
	s_waitcnt lgkmcnt(0)
	v_mfma_f32_16x16x32_bf16 v[2:5], v[130:133], v[186:189], v[2:5]
	v_mfma_f32_16x16x32_bf16 v[6:9], v[138:141], v[186:189], v[6:9]
	v_mfma_f32_16x16x32_bf16 v[30:33], v[130:133], v[194:197], v[30:33]
	v_mfma_f32_16x16x32_bf16 v[26:29], v[138:141], v[194:197], v[26:29]
	v_mfma_f32_16x16x32_bf16 v[34:37], v[130:133], v[206:209], v[34:37]
	v_mfma_f32_16x16x32_bf16 v[42:45], v[138:141], v[206:209], v[42:45]
	v_mfma_f32_16x16x32_bf16 v[62:65], v[130:133], v[214:217], v[62:65]
	v_mfma_f32_16x16x32_bf16 v[58:61], v[138:141], v[214:217], v[58:61]
	v_mfma_f32_16x16x32_bf16 v[2:5], v[134:137], v[190:193], v[2:5]
	v_mfma_f32_16x16x32_bf16 v[6:9], v[142:145], v[190:193], v[6:9]
	v_mfma_f32_16x16x32_bf16 v[30:33], v[134:137], v[198:201], v[30:33]
	v_mfma_f32_16x16x32_bf16 v[26:29], v[142:145], v[198:201], v[26:29]
	v_mfma_f32_16x16x32_bf16 v[34:37], v[134:137], v[210:213], v[34:37]
	v_mfma_f32_16x16x32_bf16 v[42:45], v[142:145], v[210:213], v[42:45]
	v_mfma_f32_16x16x32_bf16 v[62:65], v[134:137], v[238:241], v[62:65]
	v_mfma_f32_16x16x32_bf16 v[58:61], v[142:145], v[238:241], v[58:61]
	s_setprio 0
	s_setprio 1
	v_mfma_f32_16x16x32_bf16 v[14:17], v[146:149], v[186:189], v[14:17]
	v_mfma_f32_16x16x32_bf16 v[10:13], v[154:157], v[186:189], v[10:13]
	v_mfma_f32_16x16x32_bf16 v[22:25], v[146:149], v[194:197], v[22:25]
	v_mfma_f32_16x16x32_bf16 v[18:21], v[154:157], v[194:197], v[18:21]
	v_mfma_f32_16x16x32_bf16 v[46:49], v[146:149], v[206:209], v[46:49]
	v_mfma_f32_16x16x32_bf16 v[38:41], v[154:157], v[206:209], v[38:41]
	v_mfma_f32_16x16x32_bf16 v[54:57], v[146:149], v[214:217], v[54:57]
	v_mfma_f32_16x16x32_bf16 v[50:53], v[154:157], v[214:217], v[50:53]
	v_mfma_f32_16x16x32_bf16 v[14:17], v[150:153], v[190:193], v[14:17]
	v_mfma_f32_16x16x32_bf16 v[10:13], v[158:161], v[190:193], v[10:13]
	v_mfma_f32_16x16x32_bf16 v[22:25], v[150:153], v[198:201], v[22:25]
	v_mfma_f32_16x16x32_bf16 v[18:21], v[158:161], v[198:201], v[18:21]
	v_mfma_f32_16x16x32_bf16 v[46:49], v[150:153], v[210:213], v[46:49]
	v_mfma_f32_16x16x32_bf16 v[38:41], v[158:161], v[210:213], v[38:41]
	v_mfma_f32_16x16x32_bf16 v[54:57], v[150:153], v[238:241], v[54:57]
	v_mfma_f32_16x16x32_bf16 v[50:53], v[158:161], v[238:241], v[50:53]
	s_setprio 0
	s_barrier
	s_add_i32 s68, s82, s41
	v_lshl_add_u64 v[218:219], v[218:219], 0, s[76:77]
	s_mov_b32 m0, s68
	ds_read_b128 v[186:189], v204 offset:49152
	ds_read_b128 v[190:193], v204 offset:50176
	ds_read_b128 v[194:197], v204 offset:51200
	ds_read_b128 v[198:201], v204 offset:52224
	ds_read_b128 v[206:209], v204 offset:53248
	ds_read_b128 v[210:213], v204 offset:54272
	ds_read_b128 v[214:217], v204 offset:55296
	ds_read_b128 v[238:241], v204 offset:56320
	global_load_lds_dwordx4 v[218:219], off
	s_add_i32 m0, s68, 0x2000
	s_add_u32 s6, s6, 0x40080
	v_lshl_add_u64 v[218:219], v[230:231], 0, s[76:77]
	s_addc_u32 s7, s7, 0
	s_add_i32 s68, s83, s41
	global_load_lds_dwordx4 v[218:219], off
	v_lshl_add_u64 v[218:219], s[6:7], 0, v[164:165]
	s_mov_b32 m0, s68
	s_nop 0
	global_load_lds_dwordx4 v[218:219], off
	v_lshl_add_u64 v[218:219], s[6:7], 0, v[162:163]
	s_add_i32 m0, s68, 0x2000
	s_nop 0
	global_load_lds_dwordx4 v[218:219], off
	v_lshl_add_u64 v[218:219], v[232:233], 0, s[76:77]
	s_mov_b32 m0, s34
	s_nop 0
	global_load_lds_dwordx4 v[218:219], off
	v_lshl_add_u64 v[218:219], v[242:243], 0, s[76:77]
	s_mov_b32 m0, s30
	s_nop 0
	global_load_lds_dwordx4 v[218:219], off
	s_waitcnt vmcnt(8)
	s_waitcnt lgkmcnt(0)
	s_barrier
	s_setprio 1
	s_waitcnt lgkmcnt(0)
	v_mfma_f32_16x16x32_bf16 v[74:77], v[130:133], v[186:189], v[74:77]
	v_mfma_f32_16x16x32_bf16 v[70:73], v[138:141], v[186:189], v[70:73]
	v_mfma_f32_16x16x32_bf16 v[94:97], v[130:133], v[194:197], v[94:97]
	v_mfma_f32_16x16x32_bf16 v[90:93], v[138:141], v[194:197], v[90:93]
	v_mfma_f32_16x16x32_bf16 v[106:109], v[130:133], v[206:209], v[106:109]
	v_mfma_f32_16x16x32_bf16 v[102:105], v[138:141], v[206:209], v[102:105]
	v_mfma_f32_16x16x32_bf16 v[118:121], v[130:133], v[214:217], v[118:121]
	v_mfma_f32_16x16x32_bf16 v[114:117], v[138:141], v[214:217], v[114:117]
	v_mfma_f32_16x16x32_bf16 v[74:77], v[134:137], v[190:193], v[74:77]
	v_mfma_f32_16x16x32_bf16 v[70:73], v[142:145], v[190:193], v[70:73]
	v_mfma_f32_16x16x32_bf16 v[94:97], v[134:137], v[198:201], v[94:97]
	v_mfma_f32_16x16x32_bf16 v[90:93], v[142:145], v[198:201], v[90:93]
	v_mfma_f32_16x16x32_bf16 v[106:109], v[134:137], v[210:213], v[106:109]
	v_mfma_f32_16x16x32_bf16 v[102:105], v[142:145], v[210:213], v[102:105]
	v_mfma_f32_16x16x32_bf16 v[118:121], v[134:137], v[238:241], v[118:121]
	v_mfma_f32_16x16x32_bf16 v[114:117], v[142:145], v[238:241], v[114:117]
	s_setprio 0
	s_setprio 1
	v_mfma_f32_16x16x32_bf16 v[78:81], v[146:149], v[186:189], v[78:81]
	v_mfma_f32_16x16x32_bf16 v[66:69], v[154:157], v[186:189], v[66:69]
	v_mfma_f32_16x16x32_bf16 v[86:89], v[146:149], v[194:197], v[86:89]
	v_mfma_f32_16x16x32_bf16 v[82:85], v[154:157], v[194:197], v[82:85]
	v_mfma_f32_16x16x32_bf16 v[110:113], v[146:149], v[206:209], v[110:113]
	v_mfma_f32_16x16x32_bf16 v[98:101], v[154:157], v[206:209], v[98:101]
	v_mfma_f32_16x16x32_bf16 v[122:125], v[146:149], v[214:217], v[122:125]
	v_mfma_f32_16x16x32_bf16 v[126:129], v[154:157], v[214:217], v[126:129]
	v_mfma_f32_16x16x32_bf16 v[78:81], v[150:153], v[190:193], v[78:81]
	v_mfma_f32_16x16x32_bf16 v[66:69], v[158:161], v[190:193], v[66:69]
	v_mfma_f32_16x16x32_bf16 v[86:89], v[150:153], v[198:201], v[86:89]
	v_mfma_f32_16x16x32_bf16 v[82:85], v[158:161], v[198:201], v[82:85]
	v_mfma_f32_16x16x32_bf16 v[110:113], v[150:153], v[210:213], v[110:113]
	v_mfma_f32_16x16x32_bf16 v[98:101], v[158:161], v[210:213], v[98:101]
	v_mfma_f32_16x16x32_bf16 v[122:125], v[150:153], v[238:241], v[122:125]
	v_mfma_f32_16x16x32_bf16 v[126:129], v[158:161], v[238:241], v[126:129]
	s_setprio 0
	s_barrier
	s_add_i32 s59, s59, 2
	s_add_u32 s4, s4, 0x100
	s_addc_u32 s5, s5, 0
	s_add_u32 s46, s46, 0x100
	s_addc_u32 s57, s57, 0
	.p2align	6

.LBB0_490:
	s_add_i32 s3, s3, s38
	s_lshl_b32 s0, s40, 7
	s_add_u32 s4, s6, s0
	s_addc_u32 s5, s7, 0
	v_lshlrev_b32_e32 v2, 1, v192
	v_mov_b32_e32 v3, v0
	v_add_u32_e32 v1, s37, v214
	v_mov_b32_e32 v14, v0
	v_mov_b32_e32 v15, v0
	v_lshl_add_u64 v[202:203], s[4:5], 0, v[2:3]
	v_subrev_u32_e32 v240, s38, v1
	v_mov_b32_e32 v1, v0
	v_mov_b32_e32 v2, v0
	v_mov_b32_e32 v4, v0
	v_mov_b32_e32 v5, v0
	v_mov_b32_e32 v6, v0
	v_mov_b32_e32 v7, v0
	v_mov_b32_e32 v8, v0
	v_mov_b32_e32 v9, v0
	v_mov_b32_e32 v10, v0
	v_mov_b32_e32 v11, v0
	v_mov_b32_e32 v12, v0
	v_mov_b32_e32 v13, v0
	v_mov_b64_e32 v[78:79], v[14:15]
	v_mov_b64_e32 v[46:47], v[14:15]
	v_mov_b64_e32 v[62:63], v[14:15]
	v_mov_b64_e32 v[30:31], v[14:15]
	s_add_i32 s0, s27, s38
	v_mov_b64_e32 v[76:77], v[12:13]
	v_mov_b64_e32 v[74:75], v[10:11]
	v_mov_b64_e32 v[72:73], v[8:9]
	v_mov_b64_e32 v[70:71], v[6:7]
	v_mov_b64_e32 v[68:69], v[4:5]
	v_mov_b64_e32 v[66:67], v[2:3]
	v_mov_b64_e32 v[64:65], v[0:1]
	v_mov_b64_e32 v[44:45], v[12:13]
	v_mov_b64_e32 v[42:43], v[10:11]
	v_mov_b64_e32 v[40:41], v[8:9]
	v_mov_b64_e32 v[38:39], v[6:7]
	v_mov_b64_e32 v[36:37], v[4:5]
	v_mov_b64_e32 v[34:35], v[2:3]
	v_mov_b64_e32 v[32:33], v[0:1]
	v_mov_b64_e32 v[60:61], v[12:13]
	v_mov_b64_e32 v[58:59], v[10:11]
	v_mov_b64_e32 v[56:57], v[8:9]
	v_mov_b64_e32 v[54:55], v[6:7]
	v_mov_b64_e32 v[52:53], v[4:5]
	v_mov_b64_e32 v[50:51], v[2:3]
	v_mov_b64_e32 v[48:49], v[0:1]
	v_mov_b64_e32 v[28:29], v[12:13]
	v_mov_b64_e32 v[26:27], v[10:11]
	v_mov_b64_e32 v[24:25], v[8:9]
	v_mov_b64_e32 v[22:23], v[6:7]
	v_mov_b64_e32 v[20:21], v[4:5]
	v_mov_b64_e32 v[18:19], v[2:3]
	v_mov_b64_e32 v[16:17], v[0:1]
	s_waitcnt vmcnt(0)
	v_mov_b64_e32 v[2:3], v[188:189]
	v_mov_b64_e32 v[6:7], v[184:185]
	s_sub_i32 s12, s0, s37
	s_mov_b32 s14, 0
	v_mov_b32_e32 v238, 0
	v_mov_b32_e32 v242, v213
	v_mov_b32_e32 v197, v195
	v_mov_b32_e32 v239, v195
	v_mov_b32_e32 v241, 0
	v_mov_b64_e32 v[4:5], v[190:191]
	v_mov_b64_e32 v[8:9], v[186:187]
	.p2align	6

.LBB0_670:
	s_add_u32 s6, s58, 0x80
	s_addc_u32 s7, s59, 0
	s_add_u32 s21, s56, 0x100
	s_addc_u32 s26, s57, 0
	s_mov_b32 s27, 0
	s_add_i32 s46, s27, 2
	s_add_u32 s0, s6, 0x80
	s_addc_u32 s56, s7, 0
	s_add_i32 vcc_lo, 0, 0x10000
	s_cmp_eq_u32 s72, s27
	s_cselect_b32 s57, s51, s56
	s_cselect_b32 s56, s50, s0
	s_cselect_b32 s59, s53, s26
	s_cselect_b32 s58, s52, s21
	s_add_i32 s0, 0, 0x14000
	v_add_u32_e32 v70, vcc_lo, v237
	v_add_u32_e32 v94, s0, v237
	ds_read_b128 v[58:61], v70
	ds_read_b128 v[62:65], v70 offset:1024
	ds_read_b128 v[66:69], v70 offset:2048
	ds_read_b128 v[70:73], v70 offset:3072
	ds_read_b128 v[82:85], v94
	ds_read_b128 v[86:89], v94 offset:1024
	ds_read_b128 v[90:93], v94 offset:2048
	ds_read_b128 v[94:97], v94 offset:3072
	v_lshl_add_u64 v[210:211], s[6:7], 0, v[194:195]
	s_add_i32 m0, s64, 0xc000
	ds_read_b128 v[162:165], v239
	ds_read_b128 v[166:169], v239 offset:1024
	ds_read_b128 v[170:173], v239 offset:2048
	ds_read_b128 v[174:177], v239 offset:3072
	ds_read_b128 v[178:181], v239 offset:4096
	ds_read_b128 v[198:201], v239 offset:5120
	ds_read_b128 v[202:205], v239 offset:6144
	ds_read_b128 v[206:209], v239 offset:7168
	global_load_lds_dwordx4 v[210:211], off
	v_lshl_add_u64 v[210:211], s[6:7], 0, v[196:197]
	s_add_i32 m0, s64, 0xe000
	s_nop 0
	global_load_lds_dwordx4 v[210:211], off
	s_waitcnt vmcnt(8)
	s_waitcnt lgkmcnt(0)
	s_barrier
	s_setprio 1
	s_waitcnt lgkmcnt(0)
	v_mfma_f32_16x16x32_bf16 v[158:161], v[58:61], v[162:165], 0
	v_mfma_f32_16x16x32_bf16 v[154:157], v[66:69], v[162:165], 0
	v_mfma_f32_16x16x32_bf16 v[142:145], v[58:61], v[170:173], 0
	v_mfma_f32_16x16x32_bf16 v[138:141], v[66:69], v[170:173], 0
	v_mfma_f32_16x16x32_bf16 v[126:129], v[58:61], v[178:181], 0
	v_mfma_f32_16x16x32_bf16 v[122:125], v[66:69], v[178:181], 0
	v_mfma_f32_16x16x32_bf16 v[110:113], v[58:61], v[202:205], 0
	v_mfma_f32_16x16x32_bf16 v[106:109], v[66:69], v[202:205], 0
	v_mfma_f32_16x16x32_bf16 v[158:161], v[62:65], v[166:169], v[158:161]
	v_mfma_f32_16x16x32_bf16 v[154:157], v[70:73], v[166:169], v[154:157]
	v_mfma_f32_16x16x32_bf16 v[142:145], v[62:65], v[174:177], v[142:145]
	v_mfma_f32_16x16x32_bf16 v[138:141], v[70:73], v[174:177], v[138:141]
	v_mfma_f32_16x16x32_bf16 v[126:129], v[62:65], v[198:201], v[126:129]
	v_mfma_f32_16x16x32_bf16 v[122:125], v[70:73], v[198:201], v[122:125]
	v_mfma_f32_16x16x32_bf16 v[110:113], v[62:65], v[206:209], v[110:113]
	v_mfma_f32_16x16x32_bf16 v[106:109], v[70:73], v[206:209], v[106:109]
	s_setprio 0
	s_setprio 1
	v_mfma_f32_16x16x32_bf16 v[150:153], v[82:85], v[162:165], 0
	v_mfma_f32_16x16x32_bf16 v[146:149], v[90:93], v[162:165], 0
	v_mfma_f32_16x16x32_bf16 v[134:137], v[82:85], v[170:173], 0
	v_mfma_f32_16x16x32_bf16 v[130:133], v[90:93], v[170:173], 0
	v_mfma_f32_16x16x32_bf16 v[118:121], v[82:85], v[178:181], 0
	v_mfma_f32_16x16x32_bf16 v[114:117], v[90:93], v[178:181], 0
	v_mfma_f32_16x16x32_bf16 v[102:105], v[82:85], v[202:205], 0
	v_mfma_f32_16x16x32_bf16 v[98:101], v[90:93], v[202:205], 0
	v_mfma_f32_16x16x32_bf16 v[150:153], v[86:89], v[166:169], v[150:153]
	v_mfma_f32_16x16x32_bf16 v[146:149], v[94:97], v[166:169], v[146:149]
	v_mfma_f32_16x16x32_bf16 v[134:137], v[86:89], v[174:177], v[134:137]
	v_mfma_f32_16x16x32_bf16 v[130:133], v[94:97], v[174:177], v[130:133]
	v_mfma_f32_16x16x32_bf16 v[118:121], v[86:89], v[198:201], v[118:121]
	v_mfma_f32_16x16x32_bf16 v[114:117], v[94:97], v[198:201], v[114:117]
	v_mfma_f32_16x16x32_bf16 v[102:105], v[86:89], v[206:209], v[102:105]
	v_mfma_f32_16x16x32_bf16 v[98:101], v[94:97], v[206:209], v[98:101]
	s_setprio 0
	s_barrier
	s_add_i32 s27, vcc_lo, s61
	v_lshl_add_u64 v[210:211], s[58:59], 0, v[186:187]
	s_mov_b32 m0, s27
	ds_read_b128 v[162:165], v239 offset:16384
	ds_read_b128 v[166:169], v239 offset:17408
	ds_read_b128 v[170:173], v239 offset:18432
	ds_read_b128 v[174:177], v239 offset:19456
	ds_read_b128 v[178:181], v239 offset:20480
	ds_read_b128 v[198:201], v239 offset:21504
	ds_read_b128 v[202:205], v239 offset:22528
	ds_read_b128 v[206:209], v239 offset:23552
	global_load_lds_dwordx4 v[210:211], off
	s_add_i32 m0, s27, 0x2000
	v_lshl_add_u64 v[212:213], s[58:59], 0, v[182:183]
	s_add_u32 s58, s58, s12
	s_addc_u32 s59, s59, 0
	s_add_i32 s0, s0, s61
	global_load_lds_dwordx4 v[212:213], off
	v_lshl_add_u64 v[214:215], s[58:59], 0, v[186:187]
	s_mov_b32 m0, s0
	v_lshl_add_u64 v[216:217], s[58:59], 0, v[182:183]
	global_load_lds_dwordx4 v[214:215], off
	s_add_i32 m0, s0, 0x2000
	v_lshl_add_u64 v[218:219], s[56:57], 0, v[188:189]
	global_load_lds_dwordx4 v[216:217], off
	s_mov_b32 m0, s64
	v_lshl_add_u64 v[230:231], s[56:57], 0, v[184:185]
	global_load_lds_dwordx4 v[218:219], off
	s_mov_b32 m0, s65
	s_nop 0
	global_load_lds_dwordx4 v[230:231], off
	s_waitcnt vmcnt(8)
	s_waitcnt lgkmcnt(0)
	s_barrier
	s_setprio 1
	s_waitcnt lgkmcnt(0)
	v_mfma_f32_16x16x32_bf16 v[78:81], v[58:61], v[162:165], 0
	v_mfma_f32_16x16x32_bf16 v[74:77], v[66:69], v[162:165], 0
	v_mfma_f32_16x16x32_bf16 v[46:49], v[58:61], v[170:173], 0
	v_mfma_f32_16x16x32_bf16 v[42:45], v[66:69], v[170:173], 0
	v_mfma_f32_16x16x32_bf16 v[30:33], v[58:61], v[178:181], 0
	v_mfma_f32_16x16x32_bf16 v[26:29], v[66:69], v[178:181], 0
	v_mfma_f32_16x16x32_bf16 v[14:17], v[58:61], v[202:205], 0
	v_mfma_f32_16x16x32_bf16 v[10:13], v[66:69], v[202:205], 0
	v_mfma_f32_16x16x32_bf16 v[78:81], v[62:65], v[166:169], v[78:81]
	v_mfma_f32_16x16x32_bf16 v[74:77], v[70:73], v[166:169], v[74:77]
	v_mfma_f32_16x16x32_bf16 v[46:49], v[62:65], v[174:177], v[46:49]
	v_mfma_f32_16x16x32_bf16 v[42:45], v[70:73], v[174:177], v[42:45]
	v_mfma_f32_16x16x32_bf16 v[30:33], v[62:65], v[198:201], v[30:33]
	v_mfma_f32_16x16x32_bf16 v[26:29], v[70:73], v[198:201], v[26:29]
	v_mfma_f32_16x16x32_bf16 v[14:17], v[62:65], v[206:209], v[14:17]
	v_mfma_f32_16x16x32_bf16 v[10:13], v[70:73], v[206:209], v[10:13]
	s_setprio 0
	s_setprio 1
	v_mfma_f32_16x16x32_bf16 v[54:57], v[82:85], v[162:165], 0
	v_mfma_f32_16x16x32_bf16 v[50:53], v[90:93], v[162:165], 0
	v_mfma_f32_16x16x32_bf16 v[38:41], v[82:85], v[170:173], 0
	v_mfma_f32_16x16x32_bf16 v[34:37], v[90:93], v[170:173], 0
	v_mfma_f32_16x16x32_bf16 v[22:25], v[82:85], v[178:181], 0
	v_mfma_f32_16x16x32_bf16 v[18:21], v[90:93], v[178:181], 0
	v_mfma_f32_16x16x32_bf16 v[6:9], v[82:85], v[202:205], 0
	v_mfma_f32_16x16x32_bf16 v[2:5], v[90:93], v[202:205], 0
	v_mfma_f32_16x16x32_bf16 v[54:57], v[86:89], v[166:169], v[54:57]
	v_mfma_f32_16x16x32_bf16 v[50:53], v[94:97], v[166:169], v[50:53]
	v_mfma_f32_16x16x32_bf16 v[38:41], v[86:89], v[174:177], v[38:41]
	v_mfma_f32_16x16x32_bf16 v[34:37], v[94:97], v[174:177], v[34:37]
	v_mfma_f32_16x16x32_bf16 v[22:25], v[86:89], v[198:201], v[22:25]
	v_mfma_f32_16x16x32_bf16 v[18:21], v[94:97], v[198:201], v[18:21]
	v_mfma_f32_16x16x32_bf16 v[6:9], v[86:89], v[206:209], v[6:9]
	v_mfma_f32_16x16x32_bf16 v[2:5], v[94:97], v[206:209], v[2:5]
	s_setprio 0
	s_barrier
	s_add_i32 s0, 0, 0x18000
	s_add_i32 s27, 0, 0x1c000
	v_add_u32_e32 v70, s0, v237
	v_add_u32_e32 v94, s27, v237
	ds_read_b128 v[58:61], v70
	ds_read_b128 v[62:65], v70 offset:1024
	ds_read_b128 v[66:69], v70 offset:2048
	ds_read_b128 v[70:73], v70 offset:3072
	ds_read_b128 v[82:85], v94
	ds_read_b128 v[86:89], v94 offset:1024
	ds_read_b128 v[90:93], v94 offset:2048
	ds_read_b128 v[94:97], v94 offset:3072
	s_add_u32 s56, s56, s12
	s_addc_u32 s57, s57, 0
	s_mov_b32 m0, s66
	v_lshl_add_u64 v[232:233], s[56:57], 0, v[188:189]
	ds_read_b128 v[162:165], v239 offset:32768
	ds_read_b128 v[166:169], v239 offset:33792
	ds_read_b128 v[170:173], v239 offset:34816
	ds_read_b128 v[174:177], v239 offset:35840
	ds_read_b128 v[178:181], v239 offset:36864
	ds_read_b128 v[198:201], v239 offset:37888
	ds_read_b128 v[202:205], v239 offset:38912
	ds_read_b128 v[206:209], v239 offset:39936
	global_load_lds_dwordx4 v[232:233], off
	v_lshl_add_u64 v[232:233], s[56:57], 0, v[184:185]
	s_mov_b32 m0, s67
	s_nop 0
	global_load_lds_dwordx4 v[232:233], off
	s_waitcnt vmcnt(8)
	s_waitcnt lgkmcnt(0)
	s_barrier
	s_setprio 1
	s_waitcnt lgkmcnt(0)
	v_mfma_f32_16x16x32_bf16 v[158:161], v[58:61], v[162:165], v[158:161]
	v_mfma_f32_16x16x32_bf16 v[154:157], v[66:69], v[162:165], v[154:157]
	v_mfma_f32_16x16x32_bf16 v[142:145], v[58:61], v[170:173], v[142:145]
	v_mfma_f32_16x16x32_bf16 v[138:141], v[66:69], v[170:173], v[138:141]
	v_mfma_f32_16x16x32_bf16 v[126:129], v[58:61], v[178:181], v[126:129]
	v_mfma_f32_16x16x32_bf16 v[122:125], v[66:69], v[178:181], v[122:125]
	v_mfma_f32_16x16x32_bf16 v[110:113], v[58:61], v[202:205], v[110:113]
	v_mfma_f32_16x16x32_bf16 v[106:109], v[66:69], v[202:205], v[106:109]
	v_mfma_f32_16x16x32_bf16 v[158:161], v[62:65], v[166:169], v[158:161]
	v_mfma_f32_16x16x32_bf16 v[154:157], v[70:73], v[166:169], v[154:157]
	v_mfma_f32_16x16x32_bf16 v[142:145], v[62:65], v[174:177], v[142:145]
	v_mfma_f32_16x16x32_bf16 v[138:141], v[70:73], v[174:177], v[138:141]
	v_mfma_f32_16x16x32_bf16 v[126:129], v[62:65], v[198:201], v[126:129]
	v_mfma_f32_16x16x32_bf16 v[122:125], v[70:73], v[198:201], v[122:125]
	v_mfma_f32_16x16x32_bf16 v[110:113], v[62:65], v[206:209], v[110:113]
	v_mfma_f32_16x16x32_bf16 v[106:109], v[70:73], v[206:209], v[106:109]
	s_setprio 0
	s_setprio 1
	v_mfma_f32_16x16x32_bf16 v[150:153], v[82:85], v[162:165], v[150:153]
	v_mfma_f32_16x16x32_bf16 v[146:149], v[90:93], v[162:165], v[146:149]
	v_mfma_f32_16x16x32_bf16 v[134:137], v[82:85], v[170:173], v[134:137]
	v_mfma_f32_16x16x32_bf16 v[130:133], v[90:93], v[170:173], v[130:133]
	v_mfma_f32_16x16x32_bf16 v[118:121], v[82:85], v[178:181], v[118:121]
	v_mfma_f32_16x16x32_bf16 v[114:117], v[90:93], v[178:181], v[114:117]
	v_mfma_f32_16x16x32_bf16 v[102:105], v[82:85], v[202:205], v[102:105]
	v_mfma_f32_16x16x32_bf16 v[98:101], v[90:93], v[202:205], v[98:101]
	v_mfma_f32_16x16x32_bf16 v[150:153], v[86:89], v[166:169], v[150:153]
	v_mfma_f32_16x16x32_bf16 v[146:149], v[94:97], v[166:169], v[146:149]
	v_mfma_f32_16x16x32_bf16 v[134:137], v[86:89], v[174:177], v[134:137]
	v_mfma_f32_16x16x32_bf16 v[130:133], v[94:97], v[174:177], v[130:133]
	v_mfma_f32_16x16x32_bf16 v[118:121], v[86:89], v[198:201], v[118:121]
	v_mfma_f32_16x16x32_bf16 v[114:117], v[94:97], v[198:201], v[114:117]
	v_mfma_f32_16x16x32_bf16 v[102:105], v[86:89], v[206:209], v[102:105]
	v_mfma_f32_16x16x32_bf16 v[98:101], v[94:97], v[206:209], v[98:101]
	s_setprio 0
	s_barrier
	s_add_i32 s0, s0, s61
	v_lshl_add_u64 v[210:211], v[210:211], 0, s[76:77]
	s_mov_b32 m0, s0
	ds_read_b128 v[162:165], v239 offset:49152
	ds_read_b128 v[166:169], v239 offset:50176
	ds_read_b128 v[170:173], v239 offset:51200
	ds_read_b128 v[174:177], v239 offset:52224
	ds_read_b128 v[178:181], v239 offset:53248
	ds_read_b128 v[198:201], v239 offset:54272
	ds_read_b128 v[202:205], v239 offset:55296
	ds_read_b128 v[206:209], v239 offset:56320
	global_load_lds_dwordx4 v[210:211], off
	v_lshl_add_u64 v[210:211], v[212:213], 0, s[76:77]
	s_add_i32 m0, s0, 0x2000
	s_add_i32 s0, s27, s61
	global_load_lds_dwordx4 v[210:211], off
	v_lshl_add_u64 v[210:211], v[214:215], 0, s[76:77]
	s_mov_b32 m0, s0
	s_nop 0
	global_load_lds_dwordx4 v[210:211], off
	v_lshl_add_u64 v[210:211], v[216:217], 0, s[76:77]
	s_add_i32 m0, s0, 0x2000
	s_nop 0
	global_load_lds_dwordx4 v[210:211], off
	v_lshl_add_u64 v[210:211], v[218:219], 0, s[76:77]
	s_mov_b32 m0, s68
	s_nop 0
	global_load_lds_dwordx4 v[210:211], off
	v_lshl_add_u64 v[210:211], v[230:231], 0, s[76:77]
	s_mov_b32 m0, s69
	s_nop 0
	global_load_lds_dwordx4 v[210:211], off
	s_waitcnt vmcnt(8)
	s_waitcnt lgkmcnt(0)
	s_barrier
	s_setprio 1
	s_waitcnt lgkmcnt(0)
	v_mfma_f32_16x16x32_bf16 v[78:81], v[58:61], v[162:165], v[78:81]
	v_mfma_f32_16x16x32_bf16 v[74:77], v[66:69], v[162:165], v[74:77]
	v_mfma_f32_16x16x32_bf16 v[46:49], v[58:61], v[170:173], v[46:49]
	v_mfma_f32_16x16x32_bf16 v[42:45], v[66:69], v[170:173], v[42:45]
	v_mfma_f32_16x16x32_bf16 v[30:33], v[58:61], v[178:181], v[30:33]
	v_mfma_f32_16x16x32_bf16 v[26:29], v[66:69], v[178:181], v[26:29]
	v_mfma_f32_16x16x32_bf16 v[14:17], v[58:61], v[202:205], v[14:17]
	v_mfma_f32_16x16x32_bf16 v[10:13], v[66:69], v[202:205], v[10:13]
	v_mfma_f32_16x16x32_bf16 v[78:81], v[62:65], v[166:169], v[78:81]
	v_mfma_f32_16x16x32_bf16 v[74:77], v[70:73], v[166:169], v[74:77]
	v_mfma_f32_16x16x32_bf16 v[46:49], v[62:65], v[174:177], v[46:49]
	v_mfma_f32_16x16x32_bf16 v[42:45], v[70:73], v[174:177], v[42:45]
	v_mfma_f32_16x16x32_bf16 v[30:33], v[62:65], v[198:201], v[30:33]
	v_mfma_f32_16x16x32_bf16 v[26:29], v[70:73], v[198:201], v[26:29]
	v_mfma_f32_16x16x32_bf16 v[14:17], v[62:65], v[206:209], v[14:17]
	v_mfma_f32_16x16x32_bf16 v[10:13], v[70:73], v[206:209], v[10:13]
	s_setprio 0
	s_setprio 1
	v_mfma_f32_16x16x32_bf16 v[54:57], v[82:85], v[162:165], v[54:57]
	v_mfma_f32_16x16x32_bf16 v[50:53], v[90:93], v[162:165], v[50:53]
	v_mfma_f32_16x16x32_bf16 v[38:41], v[82:85], v[170:173], v[38:41]
	v_mfma_f32_16x16x32_bf16 v[34:37], v[90:93], v[170:173], v[34:37]
	v_mfma_f32_16x16x32_bf16 v[22:25], v[82:85], v[178:181], v[22:25]
	v_mfma_f32_16x16x32_bf16 v[18:21], v[90:93], v[178:181], v[18:21]
	v_mfma_f32_16x16x32_bf16 v[6:9], v[82:85], v[202:205], v[6:9]
	v_mfma_f32_16x16x32_bf16 v[2:5], v[90:93], v[202:205], v[2:5]
	v_mfma_f32_16x16x32_bf16 v[54:57], v[86:89], v[166:169], v[54:57]
	v_mfma_f32_16x16x32_bf16 v[50:53], v[94:97], v[166:169], v[50:53]
	v_mfma_f32_16x16x32_bf16 v[38:41], v[86:89], v[174:177], v[38:41]
	v_mfma_f32_16x16x32_bf16 v[34:37], v[94:97], v[174:177], v[34:37]
	v_mfma_f32_16x16x32_bf16 v[22:25], v[86:89], v[198:201], v[22:25]
	v_mfma_f32_16x16x32_bf16 v[18:21], v[94:97], v[198:201], v[18:21]
	v_mfma_f32_16x16x32_bf16 v[6:9], v[86:89], v[206:209], v[6:9]
	v_mfma_f32_16x16x32_bf16 v[2:5], v[94:97], v[206:209], v[2:5]
	s_setprio 0
	s_barrier
	s_add_u32 s6, s6, 0x100
	s_addc_u32 s7, s7, 0
	s_add_u32 s21, s21, 0x100
	s_addc_u32 s26, s26, 0
	s_mov_b32 s27, s46
	.p2align	6

.LBB0_786:
	v_mov_b32_e32 v39, v0
	v_lshl_add_u64 v[10:11], s[4:5], 0, v[38:39]
	v_mov_b32_e32 v35, v0
	v_lshl_add_u64 v[12:13], s[4:5], 0, v[34:35]
	v_mov_b32_e32 v41, v0
	s_add_i32 m0, s20, 0x18000
	v_lshl_add_u64 v[10:11], v[10:11], 0, s[76:77]
	v_lshl_add_u64 v[18:19], s[6:7], 0, v[40:41]
	v_mov_b32_e32 v37, v0
	s_waitcnt vmcnt(2)
	s_barrier
	global_load_lds_dwordx4 v[10:11], off
	v_lshl_add_u64 v[10:11], v[12:13], 0, s[76:77]
	s_add_i32 m0, s20, 0x1a000
	s_add_i32 s31, s20, 0x8000
	v_lshl_add_u64 v[20:21], s[6:7], 0, v[36:37]
	global_load_lds_dwordx4 v[10:11], off
	v_lshl_add_u64 v[10:11], v[18:19], 0, s[76:77]
	s_mov_b32 m0, s31
	s_add_i32 s34, s20, 0xa000
	v_lshl_add_u64 v[14:15], s[8:9], 0, v[38:39]
	global_load_lds_dwordx4 v[10:11], off
	v_lshl_add_u64 v[10:11], v[20:21], 0, s[76:77]
	s_mov_b32 m0, s34
	v_lshl_add_u64 v[16:17], s[8:9], 0, v[34:35]
	global_load_lds_dwordx4 v[10:11], off
	s_add_i32 m0, s20, 0x1c000
	v_lshl_add_u64 v[10:11], v[14:15], 0, s[76:77]
	global_load_lds_dwordx4 v[10:11], off
	v_lshl_add_u64 v[10:11], v[16:17], 0, s[76:77]
	s_add_i32 m0, s20, 0x1e000
	v_bfe_u32 v1, v5, 4, 2
	global_load_lds_dwordx4 v[10:11], off
	v_and_b32_e32 v9, 15, v5
	v_lshlrev_b32_e32 v22, 4, v1
	v_lshlrev_b32_e32 v5, 2, v5
	v_lshl_or_b32 v114, s15, 6, v9
	v_lshl_or_b32 v9, v9, 6, v22
	s_lshl_b32 s0, s15, 13
	v_and_b32_e32 v5, 32, v5
	v_bitop3_b32 v22, v9, s0, v5 bitop3:0xde
	s_lshl_b32 s0, s14, 5
	s_and_b32 s21, s0, 0x60
	s_lshl_b32 s0, s21, 7
	v_bitop3_b32 v54, v9, s0, v5 bitop3:0xde
	v_readlane_b32 s0, v254, 56
	s_add_i32 s35, s36, -2
	s_mul_i32 s0, s0, s1
	s_add_u32 s0, s10, s0
	s_addc_u32 s1, s11, 0
	s_add_u32 s0, s38, s0
	s_addc_u32 s1, s37, s1
	s_add_u32 s8, s0, 0x80
	v_add_u32_e32 v2, v4, v2
	s_waitcnt vmcnt(6)
	v_add_u32_e32 v5, v8, v6
	s_addc_u32 s9, s1, 0
	v_add_lshl_u32 v2, v2, v3, 1
	v_mov_b32_e32 v3, v0
	v_add_lshl_u32 v6, v5, v7, 1
	v_mov_b32_e32 v7, v0
	v_lshl_add_u64 v[52:53], s[8:9], 0, v[2:3]
	v_mov_b32_e32 v2, 0
	v_lshl_add_u64 v[50:51], s[8:9], 0, v[6:7]
	s_mov_b32 s14, 0
	s_mov_b64 s[8:9], 0
	v_add_u32_e32 v55, 0, v22
	v_mov_b32_e32 v3, v2
	v_mov_b32_e32 v4, v2
	v_mov_b32_e32 v5, v2
	v_mov_b32_e32 v6, v2
	v_mov_b32_e32 v7, v2
	v_mov_b32_e32 v8, v2
	v_mov_b32_e32 v9, v2
	v_mov_b32_e32 v18, v2
	v_mov_b32_e32 v19, v2
	v_mov_b32_e32 v20, v2
	v_mov_b32_e32 v21, v2
	v_mov_b32_e32 v22, v2
	v_mov_b32_e32 v23, v2
	v_mov_b32_e32 v24, v2
	v_mov_b32_e32 v25, v2
	v_mov_b32_e32 v42, v2
	v_mov_b32_e32 v43, v2
	v_mov_b32_e32 v44, v2
	v_mov_b32_e32 v45, v2
	v_mov_b32_e32 v46, v2
	v_mov_b32_e32 v47, v2
	v_mov_b32_e32 v48, v2
	v_mov_b32_e32 v49, v2
	v_mov_b32_e32 v82, v2
	v_mov_b32_e32 v83, v2
	v_mov_b32_e32 v84, v2
	v_mov_b32_e32 v85, v2
	v_mov_b32_e32 v86, v2
	v_mov_b32_e32 v87, v2
	v_mov_b32_e32 v88, v2
	v_mov_b32_e32 v89, v2
	v_mov_b32_e32 v10, v2
	v_mov_b32_e32 v11, v2
	v_mov_b32_e32 v12, v2
	v_mov_b32_e32 v13, v2
	v_mov_b32_e32 v14, v2
	v_mov_b32_e32 v15, v2
	v_mov_b32_e32 v16, v2
	v_mov_b32_e32 v17, v2
	v_mov_b32_e32 v26, v2
	v_mov_b32_e32 v27, v2
	v_mov_b32_e32 v28, v2
	v_mov_b32_e32 v29, v2
	v_mov_b32_e32 v30, v2
	v_mov_b32_e32 v31, v2
	v_mov_b32_e32 v32, v2
	v_mov_b32_e32 v33, v2
	v_mov_b32_e32 v70, v2
	v_mov_b32_e32 v71, v2
	v_mov_b32_e32 v72, v2
	v_mov_b32_e32 v73, v2
	v_mov_b32_e32 v78, v2
	v_mov_b32_e32 v79, v2
	v_mov_b32_e32 v80, v2
	v_mov_b32_e32 v81, v2
	v_mov_b32_e32 v90, v2
	v_mov_b32_e32 v91, v2
	v_mov_b32_e32 v92, v2
	v_mov_b32_e32 v93, v2
	v_mov_b32_e32 v94, v2
	v_mov_b32_e32 v95, v2
	v_mov_b32_e32 v96, v2
	v_mov_b32_e32 v97, v2
	s_barrier
	.p2align	6
